# P2 queue: per-XCD counters with (b,h)-grouped two-pass attention order (K/V tile sharing in L2); attention DMA issue placed differently for SIMD partner waves
# speedup vs baseline: 1.0562x; 1.0058x over previous
; __device__ __forceinline__ int launder_tid() { int x = threadIdx.x; asm volatile("" : "+v"(x)); return x; }
; #define LAS __attribute__((address_space(3)))
; DI float wave_sum(float v) { v += shx(v, 32); v += shx(v, 16); v += shx(v, 8); v += shx(v, 4); v += shx(v, 2); v += shx(v, 1); return v; }
; DI void p2_units(const Params& p, LAS unsigned char* lds, int dup) {
;     const int tid = launder_tid(), lane = tid & 63;
;     float lam;
;     { float a = p.lam_q1[lane] * p.lam_k1[lane], c = p.lam_q2[lane] * p.lam_k2[lane]; a = wave_sum(a); c = wave_sum(c); lam = __expf(a) - __expf(c) + 0.2f; }
;     unsigned* ctr = (unsigned*)(p.ws + WS_CTL) + 128 * dup;
;     LAS int* qslot = (LAS int*)(lds + LDS_BYTES - 64);
.LBB0_599:
	s_or_b64 exec, exec, s[0:1]
	v_mov_b32_e32 v0, v182
	s_barrier
	v_mbcnt_hi_u32_b32 v6, -1, v155
	v_and_b32_e32 v1, 63, v0
	v_lshlrev_b32_e32 v1, 2, v1
	global_load_dword v2, v1, s[60:61]
	global_load_dword v3, v1, s[62:63]
	global_load_dword v4, v1, s[64:65]
	global_load_dword v5, v1, s[66:67]
	v_and_b32_e32 v8, 64, v6
	v_xor_b32_e32 v7, 32, v6
	v_add_u32_e32 v8, 64, v8
	v_xor_b32_e32 v9, 16, v6
	v_cmp_lt_i32_e32 vcc, v7, v8
	v_xor_b32_e32 v10, 8, v6
	v_xor_b32_e32 v11, 4, v6
	v_cndmask_b32_e32 v7, v6, v7, vcc
	v_cmp_lt_i32_e32 vcc, v9, v8
	v_xor_b32_e32 v12, 2, v6
	v_xor_b32_e32 v13, 1, v6
	v_cndmask_b32_e32 v9, v6, v9, vcc
	v_cmp_lt_i32_e32 vcc, v10, v8
	v_lshlrev_b32_e32 v185, 2, v7
	v_lshlrev_b32_e32 v186, 2, v9
	v_cndmask_b32_e32 v10, v6, v10, vcc
	v_cmp_lt_i32_e32 vcc, v11, v8
	v_lshlrev_b32_e32 v7, 2, v10
	s_add_u32 s54, s74, 0x16418400
	v_cndmask_b32_e32 v11, v6, v11, vcc
	v_cmp_lt_i32_e32 vcc, v12, v8
	s_addc_u32 s55, s75, 0
	s_add_u32 s56, s74, 0x1a558400
	v_cndmask_b32_e32 v12, v6, v12, vcc
	v_cmp_lt_i32_e32 vcc, v13, v8
	v_lshlrev_b32_e32 v8, 2, v11
	s_addc_u32 s57, s75, 0
	s_add_u32 s58, s74, 0x184b8400
	s_addc_u32 s59, s75, 0
	s_add_u32 s0, s74, 0x1e698400
	v_writelane_b32 v254, s0, 8
	s_addc_u32 s0, s75, 0
	v_writelane_b32 v254, s0, 9
	s_add_u32 s0, s72, 0x20b00000
	v_writelane_b32 v254, s0, 10
	s_addc_u32 s0, s73, 0
	s_add_u32 s93, s74, 0x1000
	v_writelane_b32 v254, s0, 11
	s_addc_u32 s0, s75, 0
	s_add_u32 s60, s74, 0x32c58400
	s_addc_u32 s61, s75, 0
	v_writelane_b32 v254, s0, 4
	s_add_u32 s0, s72, 0x20500000
	v_writelane_b32 v254, s0, 12
	s_addc_u32 s0, s73, 0
	v_writelane_b32 v254, s0, 13
	s_add_u32 s0, s74, 0xe198400
	v_lshlrev_b32_e32 v9, 2, v12
	v_writelane_b32 v254, s0, 14
	s_addc_u32 s0, s75, 0
	v_writelane_b32 v254, s0, 15
	s_add_u32 s0, s74, 0x122d8400
	v_writelane_b32 v254, s0, 16
	s_addc_u32 s0, s75, 0
	s_add_u32 s52, s74, 0xa058400
	s_addc_u32 s53, s75, 0
	v_cndmask_b32_e32 v6, v6, v13, vcc
	v_writelane_b32 v254, s0, 17
	s_add_u32 s0, s72, 0x20700000
	v_lshlrev_b32_e32 v6, 2, v6
	v_writelane_b32 v254, s0, 18
	s_addc_u32 s0, s73, 0
	v_writelane_b32 v254, s0, 19
	s_add_u32 s0, s72, 0x20900000
	v_writelane_b32 v254, s0, 20
	s_addc_u32 s0, s73, 0
	v_writelane_b32 v254, s0, 21
	s_add_u32 s0, s74, 0x12298400
	v_writelane_b32 v254, s0, 22
	s_addc_u32 s0, s75, 0
	v_writelane_b32 v254, s0, 23
	s_add_u32 s0, s74, 0x163d8400
	v_writelane_b32 v254, s0, 24
	s_addc_u32 s0, s75, 0
	s_add_u32 s33, s74, 0x2a858400
	s_addc_u32 s84, s75, 0
	v_writelane_b32 v254, s0, 25
	s_waitcnt vmcnt(2)
	v_mul_f32_e32 v10, v2, v3
	ds_bpermute_b32 v10, v185, v10
	s_waitcnt vmcnt(0)
	v_mul_f32_e32 v11, v4, v5
	ds_bpermute_b32 v11, v185, v11
	s_add_u32 s0, s44, 0x20000
	v_writelane_b32 v254, s0, 26
	s_waitcnt lgkmcnt(1)
	v_fmac_f32_e32 v10, v2, v3
	ds_bpermute_b32 v2, v186, v10
	s_waitcnt lgkmcnt(1)
	v_fmac_f32_e32 v11, v4, v5
	ds_bpermute_b32 v3, v186, v11
	s_addc_u32 s0, s45, 0
	v_writelane_b32 v254, s0, 27
	s_waitcnt lgkmcnt(1)
	v_add_f32_e32 v2, v10, v2
	ds_bpermute_b32 v4, v7, v2
	s_waitcnt lgkmcnt(1)
	v_add_f32_e32 v3, v11, v3
	ds_bpermute_b32 v5, v7, v3
	s_add_u32 s0, s46, 0x20000
	v_writelane_b32 v254, s0, 28
	s_waitcnt lgkmcnt(1)
	v_add_f32_e32 v2, v2, v4
	ds_bpermute_b32 v4, v8, v2
	s_waitcnt lgkmcnt(1)
	v_add_f32_e32 v3, v3, v5
	ds_bpermute_b32 v5, v8, v3
	s_addc_u32 s0, s47, 0
	s_add_i32 s96, 0, 0x27fc0
	s_waitcnt lgkmcnt(1)
	v_add_f32_e32 v2, v2, v4
	ds_bpermute_b32 v4, v9, v2
	s_waitcnt lgkmcnt(1)
	v_add_f32_e32 v3, v3, v5
	ds_bpermute_b32 v5, v9, v3
	v_mov_b32_e32 v1, 0
	s_mov_b32 s85, 0xc2fc0000
	s_waitcnt lgkmcnt(1)
	v_add_f32_e32 v2, v2, v4
	ds_bpermute_b32 v4, v6, v2
	s_waitcnt lgkmcnt(1)
	v_add_f32_e32 v3, v3, v5
	ds_bpermute_b32 v5, v6, v3
	s_mov_b32 s86, 0x800000
	s_movk_i32 s78, 0x1000
	s_waitcnt lgkmcnt(1)
	v_add_f32_e32 v2, v2, v4
	v_mul_f32_e32 v2, 0x3fb8aa3b, v2
	s_waitcnt lgkmcnt(0)
	v_add_f32_e32 v3, v3, v5
	v_mul_f32_e32 v3, 0x3fb8aa3b, v3
	v_exp_f32_e32 v2, v2
	v_exp_f32_e32 v3, v3
	s_movk_i32 s79, 0x2000
	s_movk_i32 s80, 0x3000
	s_movk_i32 s81, 0x100
	v_sub_f32_e32 v2, v2, v3
	s_movk_i32 s82, 0x90
	s_movk_i32 s83, 0x140
	v_mov_b32_e32 v187, 0x358637bd
	s_mov_b32 s97, 0x2a858000
	s_movk_i32 s87, 0x110
	s_mov_b32 s88, 0xcccccccd
	s_movk_i32 s89, 0xffec
	s_mov_b32 s90, 0x78787879
	s_movk_i32 s91, 0xffef
	v_writelane_b32 v254, s0, 29
	s_add_i32 s0, 0, 0x12800
	v_add_f32_e32 v188, 0x3e4ccccd, v2
	v_mov_b32_e32 v189, 1
	v_mov_b32_e32 v190, s96
	v_mov_b32_e32 v191, 0x42800000
	v_mov_b32_e32 v192, 0x42000000
	v_mov_b32_e32 v193, 4
	v_not_b32_e32 v194, 63
	v_mov_b32_e32 v195, 3
	s_mov_b32 s63, 0
	v_cmp_eq_u32_e64 s[4:5], 0, v0
	v_writelane_b32 v254, s0, 30
	s_and_b32 s98, s2, 7
	s_lshl_b32 s98, s98, 7
	s_addk_i32 s98, 0x1800
	s_add_u32 s100, s74, s98
	s_addc_u32 s101, s75, 0
	s_branch .LBB0_603

; DI void p2_units(const Params& p, LAS unsigned char* lds, int dup) {
;     ...
;     for (;;) {
;         __syncthreads();
;         if (tid == 0) *qslot = (int)atomicAdd(ctr, 1u);
;         __syncthreads();
.LBB0_603:
	s_barrier
	s_and_saveexec_b64 s[0:1], s[4:5]
	s_cbranch_execz .LBB0_607
	s_mov_b64 s[8:9], exec
	v_mbcnt_lo_u32_b32 v0, s8, 0
	v_mbcnt_hi_u32_b32 v0, s9, v0
	v_cmp_eq_u32_e32 vcc, 0, v0
	s_and_saveexec_b64 s[6:7], vcc
	s_cbranch_execz .LBB0_606
	s_bcnt1_i32_b64 s8, s[8:9]
	v_mov_b32_e32 v2, s8
	global_atomic_add v2, v1, v2, s[100:101] sc0

; DI void p2_units(const Params& p, LAS unsigned char* lds, int dup) {
;     ...
;         __syncthreads();
;         int u = *qslot;
;         if (u >= NU_TOTAL) break;
;         if (u < NU_R1) { const int bhp = u / 7, seg = u - bhp * 7; ret_unit(p, lds, 0, bhp >> 1, bhp & 1, seg); continue; }
;         u -= NU_R1;
;         int kind = 0, bh, uu = 0;
;         if (u < NU_AS) { kind = 1; bh = u; }
;         else if (u < NU_AS + NU_A1) { const int a = u - NU_AS; bh = a & 63; uu = 31 - (a >> 6); }
;         else if (u < NU_AS + NU_A1 + NU_R2) { const int rr = u - NU_AS - NU_A1; ret_unit(p, lds, 1, (rr & 31) >> 1, rr & 1, rr >> 5); continue; }
;         else if (u < NU_AS + NU_A1 + NU_R2 + NU_A2) { const int a = u - NU_AS - NU_R2; bh = a & 63; uu = 31 - (a >> 6); }
;         else { const int rr = u - NU_AS - NU_A1 - NU_R2 - NU_A2; ret_unit(p, lds, 2, rr >> 1, rr & 1, 0); continue; }
.LBB0_607:
	s_or_b64 exec, exec, s[0:1]
	s_waitcnt lgkmcnt(0)
	s_barrier
	ds_read_b32 v0, v190
	s_movk_i32 s0, 0x147
	s_waitcnt lgkmcnt(0)
	v_cmp_lt_i32_e32 vcc, s0, v0
	v_readfirstlane_b32 s94, v0
	s_mov_b64 s[0:1], -1
	s_cbranch_vccnz .LBB0_602
	s_and_b32 s98, s2, 7
	s_cmpk_ge_u32 s94, 28
	s_cbranch_scc1 .Lq_1
	s_mul_i32 s99, s98, 28
	s_add_i32 s94, s94, s99
	s_branch .Lq_done
.Lq_1:
	s_cmpk_ge_u32 s94, 36
	s_cbranch_scc1 .Lq_2
	s_lshl_b32 s99, s98, 3
	s_add_i32 s94, s94, s99
	s_addk_i32 s94, 196
	s_branch .Lq_done
.Lq_2:
	s_cmpk_ge_u32 s94, 68
	s_cbranch_scc1 .Lq_3
	s_sub_i32 s99, s94, 36
	s_lshr_b32 s94, s99, 2
	s_lshl_b32 s94, s94, 5
	s_and_b32 s99, s99, 3
	s_add_i32 s94, s94, s99
	s_lshl_b32 s99, s98, 2
	s_add_i32 s94, s94, s99
	s_addk_i32 s94, 544
	s_branch .Lq_done
.Lq_3:
	s_cmpk_ge_u32 s94, 324
	s_cbranch_scc1 .Lq_4
	s_sub_i32 s99, s94, 68
	s_lshr_b32 s34, s99, 7
	s_lshl_b32 s34, s34, 4
	s_and_b32 s35, s99, 15
	s_or_b32 s34, s34, s35
	s_lshl_b32 s34, s34, 6
	s_bfe_u32 s35, s99, 0x30004
	s_add_i32 s34, s34, s35
	s_lshl_b32 s35, s98, 3
	s_add_i32 s34, s34, s35
	s_movk_i32 s35, 0x220
	s_cmpk_lt_u32 s34, 0x100
	s_cselect_b32 s35, 0x120, s35
	s_add_i32 s94, s34, s35
	s_branch .Lq_done
.Lq_4:
	s_lshl_b32 s99, s98, 2
	s_add_i32 s94, s94, s99
	s_addk_i32 s94, 2268
.Lq_done:
	s_cmpk_gt_i32 s94, 0xdf
	s_cbranch_scc0 .LBB0_752
	s_cmpk_lt_u32 s94, 0x120
	s_cselect_b64 s[0:1], -1, 0
	s_cmpk_gt_u32 s94, 0x11f
	s_cbranch_scc1 .LBB0_611
	s_add_i32 s34, s94, 0xffffff20
	s_mov_b64 s[64:65], -1
	s_mov_b32 s35, 0
	s_cbranch_execz .LBB0_612
	s_branch .LBB0_679

; #define LAS __attribute__((address_space(3)))
; DI s16x4 vtr(const LAS char* p) { return __builtin_bit_cast(s16x4, __builtin_amdgcn_ds_read_tr16_b64_v4i16((LAS v4i16_t*)p)); }
; DI bf16x8 cat4(s16x4 lo, s16x4 hi) { return __builtin_shufflevector(lo, hi, 0, 1, 2, 3, 4, 5, 6, 7); }
; #define MFMA32(a, b, c) __builtin_amdgcn_mfma_f32_32x32x16_bf16((a), (b), (c), 0, 0, 0)
; DI void dma_tile(LAS char* slot, const bf16_t* Kg, const bf16_t* Vg, const unsigned (&poff)[5], int wid) {
; #pragma unroll
;     for (int j = 0; j < 5; ++j) { const int g0 = wid * 5 + j, gi = g0 > 36 ? 36 : g0;
;         { const bool isk = gi < 17; glds16(isk ? (const void*)Kg : (const void*)Vg, poff[j], (unsigned)(size_t)(isk ? slot + gi * 1024 : slot + SLOT_V + (gi - 17) * 1024)); } }
; }
; DI void attn_qk(const LAS char* kb, const bf16x8 (&qf)[4], bf16x8 (&pf)[4], float& l) {
;     f32x16 zero;
; #pragma unroll
;     for (int i = 0; i < 16; ++i) zero[i] = 0.f;
;     bf16x8 k0[4], k1[4];
; #pragma unroll
;     for (int s = 0; s < 4; ++s) k0[s] = *(const LAS bf16x8*)(kb + 32 * s);
; #pragma unroll
;     for (int s = 0; s < 4; ++s) k1[s] = *(const LAS bf16x8*)(kb + 32 * KRS + 32 * s);
;     f32x16 st0 = MFMA32(k0[0], qf[0], zero), st1 = MFMA32(k1[0], qf[0], zero);
; #pragma unroll
;     for (int s = 1; s < 4; ++s) { st0 = MFMA32(k0[s], qf[s], st0); st1 = MFMA32(k1[s], qf[s], st1); }
;     SGB(0x100, 8); SGB(0x008, 8);
;     float sum = 0.f;
; #pragma unroll
;     for (int i = 0; i < 16; ++i) { const float e = __builtin_amdgcn_exp2f(st0[i]); st0[i] = e; sum += e; }
;     pf[0] = pack8(st0, 0); pf[1] = pack8(st0, 1);
; #pragma unroll
;     for (int i = 0; i < 16; ++i) { const float e = __builtin_amdgcn_exp2f(st1[i]); st1[i] = e; sum += e; }
;     pf[2] = pack8(st1, 0); pf[3] = pack8(st1, 1);
;     l += sum;
; }
; DI void attn_pv(const LAS char* vb, const bf16x8 (&pf)[4], f32x16 (&O)[4]) {
;     s16x4 va[8], vc[8];
; #pragma unroll
;     for (int ks = 0; ks < 4; ++ks) { va[2 * ks] = vtr(vb + ks * 16 * VRS); va[2 * ks + 1] = vtr(vb + (ks * 16 + 8) * VRS); }
; #pragma unroll
;     for (int ks = 0; ks < 4; ++ks) { vc[2 * ks] = vtr(vb + ks * 16 * VRS + 64); vc[2 * ks + 1] = vtr(vb + (ks * 16 + 8) * VRS + 64); }
; #pragma unroll
;     for (int ks = 0; ks < 4; ++ks) O[0] = MFMA32(cat4(va[2 * ks], va[2 * ks + 1]), pf[ks], O[0]);
.LBB0_745:
	s_add_i32 s22, s21, 3
	s_min_i32 s24, s22, s6
	s_lshl_b32 s22, s24, 6
	s_add_i32 s22, s17, s22
	s_and_b32 s24, s24, 3
	s_ashr_i32 s23, s22, 31
	s_mul_i32 s24, s24, 0x9400
	s_lshl_b64 s[22:23], s[22:23], 10
	s_add_u32 s25, s16, s22
	s_addc_u32 s26, s18, s23
	s_add_u32 s27, s19, s22
	s_addc_u32 s34, s20, s23
	s_cmp_gt_i32 s21, s29
	s_cbranch_scc1 .Lattn_skip
	s_and_b64 vcc, exec, s[0:1]
	s_cbranch_vccz .Lattn_late
	s_and_b32 s35, s21, 3
	s_mul_i32 s35, s35, 0x9400
	v_add_u32_e32 v0, s35, v174
	v_add_u32_e32 v14, s35, v134
	ds_read_b128 v[2:5], v0
	ds_read_b128 v[6:9], v0 offset:32
	ds_read_b128 v[10:13], v0 offset:64
	ds_read_b128 v[136:139], v0 offset:96
	ds_read_b128 v[140:143], v0 offset:8704
	ds_read_b128 v[144:147], v0 offset:8736
	ds_read_b128 v[148:151], v0 offset:8768
	ds_read_b128 v[196:199], v0 offset:8800
	s_and_b64 s[22:23], s[0:1], exec
	s_cselect_b32 s23, s26, s34
	s_cselect_b32 s22, s25, s27
	s_add_i32 s35, s24, s7
	s_mov_b32 m0, s35
	s_nop 0
	global_load_lds_dwordx4 v132, s[22:23]
	s_add_i32 s35, s24, s10
	s_addk_i32 s35, 0x400
	s_mov_b32 m0, s35
	s_nop 0
	global_load_lds_dwordx4 v131, s[22:23]
	s_waitcnt lgkmcnt(7)
	v_mfma_f32_32x32x16_bf16 v[96:111], v[2:5], v[112:115], 0
	ds_read_b64_tr_b16 v[200:201], v14 offset:17408
	ds_read_b64_tr_b16 v[202:203], v14 offset:19968
	s_waitcnt lgkmcnt(8)
	v_mfma_f32_32x32x16_bf16 v[96:111], v[6:9], v[116:119], v[96:111]
	ds_read_b64_tr_b16 v[204:205], v14 offset:17472
	ds_read_b64_tr_b16 v[206:207], v14 offset:20032
	s_and_b64 s[22:23], exec, s[8:9]
	s_cselect_b32 s23, s26, s34
	s_cselect_b32 s22, s25, s27
	s_add_i32 s35, s24, s11
	s_addk_i32 s35, 0x800
	s_mov_b32 m0, s35
	s_nop 0
	global_load_lds_dwordx4 v130, s[22:23]
	s_waitcnt lgkmcnt(9)
	v_mfma_f32_32x32x16_bf16 v[96:111], v[10:13], v[120:123], v[96:111]
	ds_read_b64_tr_b16 v[208:209], v14 offset:17536
	ds_read_b64_tr_b16 v[210:211], v14 offset:20096
	s_add_i32 s35, s24, s12
	s_addk_i32 s35, 0xc00
	s_mov_b32 m0, s35
	s_nop 0
	global_load_lds_dwordx4 v129, s[22:23]
	s_waitcnt lgkmcnt(10)
	v_mfma_f32_32x32x16_bf16 v[96:111], v[136:139], v[124:127], v[96:111]
	ds_read_b64_tr_b16 v[212:213], v14 offset:17600
	ds_read_b64_tr_b16 v[214:215], v14 offset:20160
	s_add_i32 s35, s24, s13
	s_addk_i32 s35, 0x1000
	s_mov_b32 m0, s35
	s_nop 0
	global_load_lds_dwordx4 v133, s[22:23]
	s_nop 0
	s_waitcnt lgkmcnt(11)
	v_mfma_f32_32x32x16_bf16 v[80:95], v[140:143], v[112:115], 0
	ds_read_b64_tr_b16 v[216:217], v14 offset:22528
	ds_read_b64_tr_b16 v[218:219], v14 offset:25088
	v_exp_f32_e32 v96, v96
	v_exp_f32_e32 v97, v97
	s_nop 0
	v_add_f32_e32 v15, v96, v97
	s_waitcnt lgkmcnt(12)
	v_mfma_f32_32x32x16_bf16 v[80:95], v[144:147], v[116:119], v[80:95]
	ds_read_b64_tr_b16 v[220:221], v14 offset:22592
	ds_read_b64_tr_b16 v[222:223], v14 offset:25152
	v_exp_f32_e32 v98, v98
	v_exp_f32_e32 v99, v99
	v_cvt_pk_bf16_f32 v96, v96, v97
	v_add_f32_e32 v15, v98, v15
	v_add_f32_e32 v15, v99, v15
	s_waitcnt lgkmcnt(13)
	v_mfma_f32_32x32x16_bf16 v[80:95], v[148:151], v[120:123], v[80:95]
	ds_read_b64_tr_b16 v[224:225], v14 offset:22656
	ds_read_b64_tr_b16 v[226:227], v14 offset:25216
	v_exp_f32_e32 v100, v100
	v_exp_f32_e32 v101, v101
	v_cvt_pk_bf16_f32 v97, v98, v99
	v_add_f32_e32 v15, v100, v15
	v_add_f32_e32 v15, v101, v15
	s_waitcnt lgkmcnt(14)
	v_mfma_f32_32x32x16_bf16 v[80:95], v[196:199], v[124:127], v[80:95]
	v_exp_f32_e32 v102, v102
	v_exp_f32_e32 v103, v103
	v_cvt_pk_bf16_f32 v98, v100, v101
	v_add_f32_e32 v15, v102, v15
	v_add_f32_e32 v15, v103, v15
	v_cvt_pk_bf16_f32 v99, v102, v103
	ds_read_b64_tr_b16 v[228:229], v14 offset:22720
	ds_read_b64_tr_b16 v[230:231], v14 offset:25280
	s_waitcnt lgkmcnt(14)
	v_mfma_f32_32x32x16_bf16 v[64:79], v[200:203], v[96:99], v[64:79]
	ds_read_b64_tr_b16 v[232:233], v14 offset:27648
	ds_read_b64_tr_b16 v[234:235], v14 offset:30208
	v_exp_f32_e32 v104, v104
	v_exp_f32_e32 v105, v105
	s_nop 0
	v_add_f32_e32 v15, v104, v15
	v_add_f32_e32 v15, v105, v15
	s_waitcnt lgkmcnt(14)
	v_mfma_f32_32x32x16_bf16 v[48:63], v[204:207], v[96:99], v[48:63]
	ds_read_b64_tr_b16 v[236:237], v14 offset:27712
	ds_read_b64_tr_b16 v[238:239], v14 offset:30272
	v_exp_f32_e32 v106, v106
	v_exp_f32_e32 v107, v107
	v_cvt_pk_bf16_f32 v104, v104, v105
	v_add_f32_e32 v15, v106, v15
	v_add_f32_e32 v15, v107, v15
	s_waitcnt lgkmcnt(14)
	v_mfma_f32_32x32x16_bf16 v[32:47], v[208:211], v[96:99], v[32:47]
	ds_read_b64_tr_b16 v[240:241], v14 offset:27776
	ds_read_b64_tr_b16 v[242:243], v14 offset:30336
	v_exp_f32_e32 v108, v108
	v_exp_f32_e32 v109, v109
	v_cvt_pk_bf16_f32 v105, v106, v107
	v_add_f32_e32 v15, v108, v15
	v_add_f32_e32 v15, v109, v15
	s_waitcnt lgkmcnt(14)
	v_mfma_f32_32x32x16_bf16 v[16:31], v[212:215], v[96:99], v[16:31]
	v_exp_f32_e32 v110, v110
	v_exp_f32_e32 v111, v111
	v_cvt_pk_bf16_f32 v106, v108, v109
	v_add_f32_e32 v15, v110, v15
	v_add_f32_e32 v15, v111, v15
	v_cvt_pk_bf16_f32 v107, v110, v111
	ds_read_b64_tr_b16 v[244:245], v14 offset:27840
	ds_read_b64_tr_b16 v[246:247], v14 offset:30400
	s_waitcnt lgkmcnt(14)
	v_mfma_f32_32x32x16_bf16 v[64:79], v[216:219], v[104:107], v[64:79]
	ds_read_b64_tr_b16 v[248:249], v14 offset:32768
	ds_read_b64_tr_b16 v[250:251], v14 offset:35328
	v_exp_f32_e32 v80, v80
	v_exp_f32_e32 v81, v81
	s_nop 0
	v_add_f32_e32 v15, v80, v15
	v_add_f32_e32 v15, v81, v15
	s_waitcnt lgkmcnt(14)
	v_mfma_f32_32x32x16_bf16 v[48:63], v[220:223], v[104:107], v[48:63]
	ds_read_b64_tr_b16 v[2:3], v14 offset:32832
	ds_read_b64_tr_b16 v[4:5], v14 offset:35392
	v_exp_f32_e32 v82, v82
	v_exp_f32_e32 v83, v83
	v_cvt_pk_bf16_f32 v80, v80, v81
	v_add_f32_e32 v15, v82, v15
	v_add_f32_e32 v15, v83, v15
	s_waitcnt lgkmcnt(14)
; #define LAS __attribute__((address_space(3)))
; DI s16x4 vtr(const LAS char* p) { return __builtin_bit_cast(s16x4, __builtin_amdgcn_ds_read_tr16_b64_v4i16((LAS v4i16_t*)p)); }
; DI bf16x8 cat4(s16x4 lo, s16x4 hi) { return __builtin_shufflevector(lo, hi, 0, 1, 2, 3, 4, 5, 6, 7); }
; #define SGB(mask, n) __builtin_amdgcn_sched_group_barrier((mask), (n), 0)
; DI void attn_qk(const LAS char* kb, const bf16x8 (&qf)[4], bf16x8 (&pf)[4], float& l) {
;     ...
;     f32x16 st0 = MFMA32(k0[0], qf[0], zero), st1 = MFMA32(k1[0], qf[0], zero);
; #pragma unroll
;     for (int s = 1; s < 4; ++s) { st0 = MFMA32(k0[s], qf[s], st0); st1 = MFMA32(k1[s], qf[s], st1); }
;     SGB(0x100, 8); SGB(0x008, 8);
;     float sum = 0.f;
; #pragma unroll
;     for (int i = 0; i < 16; ++i) { const float e = __builtin_amdgcn_exp2f(st0[i]); st0[i] = e; sum += e; }
;     pf[0] = pack8(st0, 0); pf[1] = pack8(st0, 1);
; #pragma unroll
;     for (int i = 0; i < 16; ++i) { const float e = __builtin_amdgcn_exp2f(st1[i]); st1[i] = e; sum += e; }
;     pf[2] = pack8(st1, 0); pf[3] = pack8(st1, 1);
;     l += sum;
; }
; DI void attn_pv(const LAS char* vb, const bf16x8 (&pf)[4], f32x16 (&O)[4]) {
;     s16x4 va[8], vc[8];
; #pragma unroll
;     for (int ks = 0; ks < 4; ++ks) { va[2 * ks] = vtr(vb + ks * 16 * VRS); va[2 * ks + 1] = vtr(vb + (ks * 16 + 8) * VRS); }
; #pragma unroll
;     for (int ks = 0; ks < 4; ++ks) { vc[2 * ks] = vtr(vb + ks * 16 * VRS + 64); vc[2 * ks + 1] = vtr(vb + (ks * 16 + 8) * VRS + 64); }
; #pragma unroll
;     for (int ks = 0; ks < 4; ++ks) O[0] = MFMA32(cat4(va[2 * ks], va[2 * ks + 1]), pf[ks], O[0]);
; #pragma unroll
;     for (int ks = 0; ks < 4; ++ks) { va[2 * ks] = vtr(vb + ks * 16 * VRS + 128); va[2 * ks + 1] = vtr(vb + (ks * 16 + 8) * VRS + 128); }
;     SGB(0x100, 16); SGB(0x008, 4); SGB(0x100, 8);
; #pragma unroll
;     for (int ks = 0; ks < 4; ++ks) O[1] = MFMA32(cat4(vc[2 * ks], vc[2 * ks + 1]), pf[ks], O[1]);
; #pragma unroll
;     for (int ks = 0; ks < 4; ++ks) { vc[2 * ks] = vtr(vb + ks * 16 * VRS + 192); vc[2 * ks + 1] = vtr(vb + (ks * 16 + 8) * VRS + 192); }
;     SGB(0x008, 4); SGB(0x100, 8);
; #pragma unroll
;     for (int ks = 0; ks < 4; ++ks) O[2] = MFMA32(cat4(va[2 * ks], va[2 * ks + 1]), pf[ks], O[2]);
;     SGB(0x008, 4);
; #pragma unroll
;     for (int ks = 0; ks < 4; ++ks) O[3] = MFMA32(cat4(vc[2 * ks], vc[2 * ks + 1]), pf[ks], O[3]);
;     SGB(0x008, 4);
	v_mfma_f32_32x32x16_bf16 v[32:47], v[224:227], v[104:107], v[32:47]
	ds_read_b64_tr_b16 v[6:7], v14 offset:32896
	ds_read_b64_tr_b16 v[8:9], v14 offset:35456
	v_exp_f32_e32 v84, v84
	v_exp_f32_e32 v85, v85
	v_cvt_pk_bf16_f32 v81, v82, v83
	v_add_f32_e32 v15, v84, v15
	v_add_f32_e32 v15, v85, v15
	s_waitcnt lgkmcnt(14)
	v_mfma_f32_32x32x16_bf16 v[16:31], v[228:231], v[104:107], v[16:31]
	v_exp_f32_e32 v86, v86
	v_exp_f32_e32 v87, v87
	v_cvt_pk_bf16_f32 v82, v84, v85
	v_add_f32_e32 v15, v86, v15
	v_add_f32_e32 v15, v87, v15
	v_cvt_pk_bf16_f32 v83, v86, v87
	ds_read_b64_tr_b16 v[10:11], v14 offset:32960
	ds_read_b64_tr_b16 v[12:13], v14 offset:35520
	s_waitcnt lgkmcnt(14)
	v_mfma_f32_32x32x16_bf16 v[64:79], v[232:235], v[80:83], v[64:79]
	v_exp_f32_e32 v88, v88
	v_exp_f32_e32 v89, v89
	s_nop 0
	v_add_f32_e32 v15, v88, v15
	v_add_f32_e32 v15, v89, v15
	s_waitcnt lgkmcnt(12)
	v_mfma_f32_32x32x16_bf16 v[48:63], v[236:239], v[80:83], v[48:63]
	v_exp_f32_e32 v90, v90
	v_exp_f32_e32 v91, v91
	v_cvt_pk_bf16_f32 v88, v88, v89
	v_add_f32_e32 v15, v90, v15
	v_add_f32_e32 v15, v91, v15
	s_waitcnt lgkmcnt(10)
	v_mfma_f32_32x32x16_bf16 v[32:47], v[240:243], v[80:83], v[32:47]
	v_exp_f32_e32 v92, v92
	v_exp_f32_e32 v93, v93
	v_cvt_pk_bf16_f32 v89, v90, v91
	v_add_f32_e32 v15, v92, v15
	v_add_f32_e32 v15, v93, v15
	s_waitcnt lgkmcnt(8)
	v_mfma_f32_32x32x16_bf16 v[16:31], v[244:247], v[80:83], v[16:31]
	v_exp_f32_e32 v94, v94
	v_exp_f32_e32 v95, v95
	v_cvt_pk_bf16_f32 v90, v92, v93
	v_add_f32_e32 v15, v94, v15
	v_add_f32_e32 v15, v95, v15
	v_cvt_pk_bf16_f32 v91, v94, v95
	v_add_f32_e32 v175, v175, v15
	s_nop 0
	s_waitcnt lgkmcnt(6)
	v_mfma_f32_32x32x16_bf16 v[64:79], v[248:251], v[88:91], v[64:79]
	s_waitcnt lgkmcnt(4)
	v_mfma_f32_32x32x16_bf16 v[48:63], v[2:5], v[88:91], v[48:63]
	s_waitcnt lgkmcnt(2)
	v_mfma_f32_32x32x16_bf16 v[32:47], v[6:9], v[88:91], v[32:47]
	s_waitcnt lgkmcnt(0)
	v_mfma_f32_32x32x16_bf16 v[16:31], v[10:13], v[88:91], v[16:31]
	s_branch .LBB0_744
.Lattn_late:
	s_and_b32 s35, s21, 3
	s_mul_i32 s35, s35, 0x9400
	v_add_u32_e32 v0, s35, v174
	v_add_u32_e32 v14, s35, v134
	ds_read_b128 v[2:5], v0
	ds_read_b128 v[6:9], v0 offset:32
	ds_read_b128 v[10:13], v0 offset:64
	ds_read_b128 v[136:139], v0 offset:96
	ds_read_b128 v[140:143], v0 offset:8704
	ds_read_b128 v[144:147], v0 offset:8736
	ds_read_b128 v[148:151], v0 offset:8768
	ds_read_b128 v[196:199], v0 offset:8800
	s_waitcnt lgkmcnt(7)
	v_mfma_f32_32x32x16_bf16 v[96:111], v[2:5], v[112:115], 0
	ds_read_b64_tr_b16 v[200:201], v14 offset:17408
	ds_read_b64_tr_b16 v[202:203], v14 offset:19968
	s_waitcnt lgkmcnt(8)
	v_mfma_f32_32x32x16_bf16 v[96:111], v[6:9], v[116:119], v[96:111]
	ds_read_b64_tr_b16 v[204:205], v14 offset:17472
	ds_read_b64_tr_b16 v[206:207], v14 offset:20032
	s_waitcnt lgkmcnt(9)
	v_mfma_f32_32x32x16_bf16 v[96:111], v[10:13], v[120:123], v[96:111]
	ds_read_b64_tr_b16 v[208:209], v14 offset:17536
	ds_read_b64_tr_b16 v[210:211], v14 offset:20096
	s_waitcnt lgkmcnt(10)
	v_mfma_f32_32x32x16_bf16 v[96:111], v[136:139], v[124:127], v[96:111]
	ds_read_b64_tr_b16 v[212:213], v14 offset:17600
	ds_read_b64_tr_b16 v[214:215], v14 offset:20160
	s_nop 5
	s_waitcnt lgkmcnt(11)
	v_mfma_f32_32x32x16_bf16 v[80:95], v[140:143], v[112:115], 0
	ds_read_b64_tr_b16 v[216:217], v14 offset:22528
	ds_read_b64_tr_b16 v[218:219], v14 offset:25088
	v_exp_f32_e32 v96, v96
	v_exp_f32_e32 v97, v97
	s_nop 0
	v_add_f32_e32 v15, v96, v97
	s_waitcnt lgkmcnt(12)
	v_mfma_f32_32x32x16_bf16 v[80:95], v[144:147], v[116:119], v[80:95]
	ds_read_b64_tr_b16 v[220:221], v14 offset:22592
	ds_read_b64_tr_b16 v[222:223], v14 offset:25152
	v_exp_f32_e32 v98, v98
	v_exp_f32_e32 v99, v99
	v_cvt_pk_bf16_f32 v96, v96, v97
	v_add_f32_e32 v15, v98, v15
	v_add_f32_e32 v15, v99, v15
	s_waitcnt lgkmcnt(13)
	v_mfma_f32_32x32x16_bf16 v[80:95], v[148:151], v[120:123], v[80:95]
	ds_read_b64_tr_b16 v[224:225], v14 offset:22656
	ds_read_b64_tr_b16 v[226:227], v14 offset:25216
	v_exp_f32_e32 v100, v100
	v_exp_f32_e32 v101, v101
	v_cvt_pk_bf16_f32 v97, v98, v99
	v_add_f32_e32 v15, v100, v15
	v_add_f32_e32 v15, v101, v15
	s_waitcnt lgkmcnt(14)
	v_mfma_f32_32x32x16_bf16 v[80:95], v[196:199], v[124:127], v[80:95]
	v_exp_f32_e32 v102, v102
	v_exp_f32_e32 v103, v103
	v_cvt_pk_bf16_f32 v98, v100, v101
	v_add_f32_e32 v15, v102, v15
	v_add_f32_e32 v15, v103, v15
	v_cvt_pk_bf16_f32 v99, v102, v103
	ds_read_b64_tr_b16 v[228:229], v14 offset:22720
	ds_read_b64_tr_b16 v[230:231], v14 offset:25280
	s_waitcnt lgkmcnt(14)
; #define LAS __attribute__((address_space(3)))
; DI s16x4 vtr(const LAS char* p) { return __builtin_bit_cast(s16x4, __builtin_amdgcn_ds_read_tr16_b64_v4i16((LAS v4i16_t*)p)); }
; DI bf16x8 cat4(s16x4 lo, s16x4 hi) { return __builtin_shufflevector(lo, hi, 0, 1, 2, 3, 4, 5, 6, 7); }
; #define MFMA32(a, b, c) __builtin_amdgcn_mfma_f32_32x32x16_bf16((a), (b), (c), 0, 0, 0)
; #define SGB(mask, n) __builtin_amdgcn_sched_group_barrier((mask), (n), 0)
; DI void dma_tile(LAS char* slot, const bf16_t* Kg, const bf16_t* Vg, const unsigned (&poff)[5], int wid) {
; #pragma unroll
;     for (int j = 0; j < 5; ++j) { const int g0 = wid * 5 + j, gi = g0 > 36 ? 36 : g0;
;         { const bool isk = gi < 17; glds16(isk ? (const void*)Kg : (const void*)Vg, poff[j], (unsigned)(size_t)(isk ? slot + gi * 1024 : slot + SLOT_V + (gi - 17) * 1024)); } }
; DI void attn_pv(const LAS char* vb, const bf16x8 (&pf)[4], f32x16 (&O)[4]) {
;     s16x4 va[8], vc[8];
; #pragma unroll
;     for (int ks = 0; ks < 4; ++ks) { va[2 * ks] = vtr(vb + ks * 16 * VRS); va[2 * ks + 1] = vtr(vb + (ks * 16 + 8) * VRS); }
; #pragma unroll
;     for (int ks = 0; ks < 4; ++ks) { vc[2 * ks] = vtr(vb + ks * 16 * VRS + 64); vc[2 * ks + 1] = vtr(vb + (ks * 16 + 8) * VRS + 64); }
; #pragma unroll
;     for (int ks = 0; ks < 4; ++ks) O[0] = MFMA32(cat4(va[2 * ks], va[2 * ks + 1]), pf[ks], O[0]);
; #pragma unroll
;     for (int ks = 0; ks < 4; ++ks) { va[2 * ks] = vtr(vb + ks * 16 * VRS + 128); va[2 * ks + 1] = vtr(vb + (ks * 16 + 8) * VRS + 128); }
;     SGB(0x100, 16); SGB(0x008, 4); SGB(0x100, 8);
; #pragma unroll
;     for (int ks = 0; ks < 4; ++ks) O[1] = MFMA32(cat4(vc[2 * ks], vc[2 * ks + 1]), pf[ks], O[1]);
; #pragma unroll
;     for (int ks = 0; ks < 4; ++ks) { vc[2 * ks] = vtr(vb + ks * 16 * VRS + 192); vc[2 * ks + 1] = vtr(vb + (ks * 16 + 8) * VRS + 192); }
;     SGB(0x008, 4); SGB(0x100, 8);
; #pragma unroll
;     for (int ks = 0; ks < 4; ++ks) O[2] = MFMA32(cat4(va[2 * ks], va[2 * ks + 1]), pf[ks], O[2]);
;     SGB(0x008, 4);
; #pragma unroll
;     for (int ks = 0; ks < 4; ++ks) O[3] = MFMA32(cat4(vc[2 * ks], vc[2 * ks + 1]), pf[ks], O[3]);
;     SGB(0x008, 4);
	v_mfma_f32_32x32x16_bf16 v[64:79], v[200:203], v[96:99], v[64:79]
	ds_read_b64_tr_b16 v[232:233], v14 offset:27648
	ds_read_b64_tr_b16 v[234:235], v14 offset:30208
	v_exp_f32_e32 v104, v104
	v_exp_f32_e32 v105, v105
	s_nop 0
	v_add_f32_e32 v15, v104, v15
	v_add_f32_e32 v15, v105, v15
	s_waitcnt lgkmcnt(14)
	v_mfma_f32_32x32x16_bf16 v[48:63], v[204:207], v[96:99], v[48:63]
	ds_read_b64_tr_b16 v[236:237], v14 offset:27712
	ds_read_b64_tr_b16 v[238:239], v14 offset:30272
	v_exp_f32_e32 v106, v106
	v_exp_f32_e32 v107, v107
	v_cvt_pk_bf16_f32 v104, v104, v105
	v_add_f32_e32 v15, v106, v15
	v_add_f32_e32 v15, v107, v15
	s_waitcnt lgkmcnt(14)
	v_mfma_f32_32x32x16_bf16 v[32:47], v[208:211], v[96:99], v[32:47]
	ds_read_b64_tr_b16 v[240:241], v14 offset:27776
	ds_read_b64_tr_b16 v[242:243], v14 offset:30336
	v_exp_f32_e32 v108, v108
	v_exp_f32_e32 v109, v109
	v_cvt_pk_bf16_f32 v105, v106, v107
	v_add_f32_e32 v15, v108, v15
	v_add_f32_e32 v15, v109, v15
	s_waitcnt lgkmcnt(14)
	v_mfma_f32_32x32x16_bf16 v[16:31], v[212:215], v[96:99], v[16:31]
	v_exp_f32_e32 v110, v110
	v_exp_f32_e32 v111, v111
	v_cvt_pk_bf16_f32 v106, v108, v109
	v_add_f32_e32 v15, v110, v15
	v_add_f32_e32 v15, v111, v15
	v_cvt_pk_bf16_f32 v107, v110, v111
	ds_read_b64_tr_b16 v[244:245], v14 offset:27840
	ds_read_b64_tr_b16 v[246:247], v14 offset:30400
	s_waitcnt lgkmcnt(14)
	v_mfma_f32_32x32x16_bf16 v[64:79], v[216:219], v[104:107], v[64:79]
	ds_read_b64_tr_b16 v[248:249], v14 offset:32768
	ds_read_b64_tr_b16 v[250:251], v14 offset:35328
	s_and_b64 s[22:23], s[0:1], exec
	s_cselect_b32 s23, s26, s34
	s_cselect_b32 s22, s25, s27
	s_add_i32 s35, s24, s7
	s_mov_b32 m0, s35
	s_nop 0
	global_load_lds_dwordx4 v132, s[22:23]
	v_exp_f32_e32 v80, v80
	v_exp_f32_e32 v81, v81
	s_nop 0
	v_add_f32_e32 v15, v80, v15
	v_add_f32_e32 v15, v81, v15
	s_waitcnt lgkmcnt(14)
	v_mfma_f32_32x32x16_bf16 v[48:63], v[220:223], v[104:107], v[48:63]
	ds_read_b64_tr_b16 v[2:3], v14 offset:32832
	ds_read_b64_tr_b16 v[4:5], v14 offset:35392
	v_exp_f32_e32 v82, v82
	v_exp_f32_e32 v83, v83
	v_cvt_pk_bf16_f32 v80, v80, v81
	v_add_f32_e32 v15, v82, v15
	v_add_f32_e32 v15, v83, v15
	s_waitcnt lgkmcnt(14)
	v_mfma_f32_32x32x16_bf16 v[32:47], v[224:227], v[104:107], v[32:47]
	ds_read_b64_tr_b16 v[6:7], v14 offset:32896
	ds_read_b64_tr_b16 v[8:9], v14 offset:35456
	s_add_i32 s35, s24, s10
	s_addk_i32 s35, 0x400
	s_mov_b32 m0, s35
	s_nop 0
	global_load_lds_dwordx4 v131, s[22:23]
	v_exp_f32_e32 v84, v84
	v_exp_f32_e32 v85, v85
	v_cvt_pk_bf16_f32 v81, v82, v83
	v_add_f32_e32 v15, v84, v15
	v_add_f32_e32 v15, v85, v15
	s_waitcnt lgkmcnt(14)
	v_mfma_f32_32x32x16_bf16 v[16:31], v[228:231], v[104:107], v[16:31]
	v_exp_f32_e32 v86, v86
	v_exp_f32_e32 v87, v87
	v_cvt_pk_bf16_f32 v82, v84, v85
	v_add_f32_e32 v15, v86, v15
	v_add_f32_e32 v15, v87, v15
	v_cvt_pk_bf16_f32 v83, v86, v87
	ds_read_b64_tr_b16 v[10:11], v14 offset:32960
	ds_read_b64_tr_b16 v[12:13], v14 offset:35520
	s_waitcnt lgkmcnt(14)
	v_mfma_f32_32x32x16_bf16 v[64:79], v[232:235], v[80:83], v[64:79]
	s_and_b64 s[22:23], exec, s[8:9]
	s_cselect_b32 s23, s26, s34
	s_cselect_b32 s22, s25, s27
	s_add_i32 s35, s24, s11
	s_addk_i32 s35, 0x800
	s_mov_b32 m0, s35
	s_nop 0
	global_load_lds_dwordx4 v130, s[22:23]
	v_exp_f32_e32 v88, v88
	v_exp_f32_e32 v89, v89
	s_nop 0
	v_add_f32_e32 v15, v88, v15
	v_add_f32_e32 v15, v89, v15
	s_waitcnt lgkmcnt(12)
	v_mfma_f32_32x32x16_bf16 v[48:63], v[236:239], v[80:83], v[48:63]
	v_exp_f32_e32 v90, v90
	v_exp_f32_e32 v91, v91
	v_cvt_pk_bf16_f32 v88, v88, v89
	v_add_f32_e32 v15, v90, v15
	v_add_f32_e32 v15, v91, v15
	s_waitcnt lgkmcnt(10)
	v_mfma_f32_32x32x16_bf16 v[32:47], v[240:243], v[80:83], v[32:47]
	s_add_i32 s35, s24, s12
	s_addk_i32 s35, 0xc00
	s_mov_b32 m0, s35
	s_nop 0
	global_load_lds_dwordx4 v129, s[22:23]
	v_exp_f32_e32 v92, v92
	v_exp_f32_e32 v93, v93
	v_cvt_pk_bf16_f32 v89, v90, v91
	v_add_f32_e32 v15, v92, v15
	v_add_f32_e32 v15, v93, v15
	s_waitcnt lgkmcnt(8)
	v_mfma_f32_32x32x16_bf16 v[16:31], v[244:247], v[80:83], v[16:31]
	v_exp_f32_e32 v94, v94
	v_exp_f32_e32 v95, v95
	v_cvt_pk_bf16_f32 v90, v92, v93
	v_add_f32_e32 v15, v94, v15
	v_add_f32_e32 v15, v95, v15
	v_cvt_pk_bf16_f32 v91, v94, v95
	v_add_f32_e32 v175, v175, v15
	s_nop 0
	s_waitcnt lgkmcnt(6)
	v_mfma_f32_32x32x16_bf16 v[64:79], v[248:251], v[88:91], v[64:79]
	s_add_i32 s35, s24, s13
	s_addk_i32 s35, 0x1000
	s_mov_b32 m0, s35
	s_nop 0
	global_load_lds_dwordx4 v133, s[22:23]
	s_waitcnt lgkmcnt(4)
	v_mfma_f32_32x32x16_bf16 v[48:63], v[2:5], v[88:91], v[48:63]
	s_waitcnt lgkmcnt(2)
	v_mfma_f32_32x32x16_bf16 v[32:47], v[6:9], v[88:91], v[32:47]
	s_waitcnt lgkmcnt(0)
	v_mfma_f32_32x32x16_bf16 v[16:31], v[10:13], v[88:91], v[16:31]
	s_branch .LBB0_744

; template <int LO, int HI> __global__ void __launch_bounds__(512) hymba_fwd(Params p) {
;     extern __shared__ __attribute__((aligned(16))) unsigned char smem[];
	.amdhsa_kernel _Z9hymba_fwdILi0ELi6EEv6Params
		.amdhsa_group_segment_fixed_size 0
		.amdhsa_private_segment_fixed_size 0
		.amdhsa_kernarg_size 440
		.amdhsa_user_sgpr_count 2
		.amdhsa_user_sgpr_dispatch_ptr 0
		.amdhsa_user_sgpr_queue_ptr 0
		.amdhsa_user_sgpr_kernarg_segment_ptr 1
		.amdhsa_user_sgpr_dispatch_id 0
		.amdhsa_user_sgpr_kernarg_preload_length 0
		.amdhsa_user_sgpr_kernarg_preload_offset 0
		.amdhsa_user_sgpr_private_segment_size 0
		.amdhsa_uses_dynamic_stack 0
		.amdhsa_enable_private_segment 0
		.amdhsa_system_sgpr_workgroup_id_x 1
		.amdhsa_system_sgpr_workgroup_id_y 0
		.amdhsa_system_sgpr_workgroup_id_z 0
		.amdhsa_system_sgpr_workgroup_info 0
		.amdhsa_system_vgpr_workitem_id 2
		.amdhsa_next_free_vgpr 255
		.amdhsa_next_free_sgpr 102
		.amdhsa_accum_offset 256
		.amdhsa_reserve_vcc 1
		.amdhsa_float_round_mode_32 0
		.amdhsa_float_round_mode_16_64 0
		.amdhsa_float_denorm_mode_32 3
		.amdhsa_float_denorm_mode_16_64 3
		.amdhsa_dx10_clamp 1
		.amdhsa_ieee_mode 1
		.amdhsa_fp16_overflow 0
		.amdhsa_tg_split 0
		.amdhsa_exception_fp_ieee_invalid_op 0
		.amdhsa_exception_fp_denorm_src 0
		.amdhsa_exception_fp_ieee_div_zero 0
		.amdhsa_exception_fp_ieee_overflow 0
		.amdhsa_exception_fp_ieee_underflow 0
		.amdhsa_exception_fp_ieee_inexact 0
		.amdhsa_exception_int_div_zero 0
	.end_amdhsa_kernel

; template <int LO, int HI> __global__ void __launch_bounds__(512) hymba_fwd(Params p) {
;     extern __shared__ __attribute__((aligned(16))) unsigned char smem[];
amdhsa.kernels:
  - .agpr_count:     0
    .args:
      - .offset:         0
        .size:           184
        .value_kind:     by_value
      - .offset:         184
        .size:           4
        .value_kind:     hidden_block_count_x
      - .offset:         188
        .size:           4
        .value_kind:     hidden_block_count_y
      - .offset:         192
        .size:           4
        .value_kind:     hidden_block_count_z
      - .offset:         196
        .size:           2
        .value_kind:     hidden_group_size_x
      - .offset:         198
        .size:           2
        .value_kind:     hidden_group_size_y
      - .offset:         200
        .size:           2
        .value_kind:     hidden_group_size_z
      - .offset:         202
        .size:           2
        .value_kind:     hidden_remainder_x
      - .offset:         204
        .size:           2
        .value_kind:     hidden_remainder_y
      - .offset:         206
        .size:           2
        .value_kind:     hidden_remainder_z
      - .offset:         224
        .size:           8
        .value_kind:     hidden_global_offset_x
      - .offset:         232
        .size:           8
        .value_kind:     hidden_global_offset_y
      - .offset:         240
        .size:           8
        .value_kind:     hidden_global_offset_z
      - .offset:         248
        .size:           2
        .value_kind:     hidden_grid_dims
      - .offset:         272
        .size:           8
        .value_kind:     hidden_multigrid_sync_arg
      - .offset:         304
        .size:           4
        .value_kind:     hidden_dynamic_lds_size
    .group_segment_fixed_size: 0
    .kernarg_segment_align: 8
    .kernarg_segment_size: 440
    .language:       OpenCL C
    .language_version:
      - 2
      - 0
    .max_flat_workgroup_size: 512
    .name:           _Z9hymba_fwdILi0ELi6EEv6Params
    .private_segment_fixed_size: 0
    .sgpr_count:     108
    .sgpr_spill_count: 35
    .symbol:         _Z9hymba_fwdILi0ELi6EEv6Params.kd
    .uniform_work_group_size: 1
    .uses_dynamic_stack: false
    .vgpr_count:     255
    .vgpr_spill_count: 0
    .wavefront_size: 64
